# grid barrier: non-leader workgroups poll the cross-XCD generation word directly, leader skips per-XCD release add
# baseline (speedup 1.0000x reference)
; __device__ __forceinline__ unsigned xb_ld(unsigned* p)              { return __hip_atomic_load(p, __ATOMIC_RELAXED, __HIP_MEMORY_SCOPE_AGENT); }
; __device__ __forceinline__ unsigned xb_add(unsigned* p, unsigned v) { return __hip_atomic_fetch_add(p, v, __ATOMIC_RELAXED, __HIP_MEMORY_SCOPE_AGENT); }
; #define XB_SPIN(cond, bar) do { unsigned _sp = 0; while (cond) { __builtin_amdgcn_s_sleep(1); \
;     if ((++_sp & 255u) == 0u) { if (xb_ld(&(bar)[XB_TMO])) break; if (_sp > XB_SPIN_CAP) { atomicAdd(&(bar)[XB_TMO], 1u); break; } } } } while (0)
; __device__ __forceinline__ void xcd_barrier(const XcdBarrier& b) {
;     ...
;         const unsigned old = xb_add(&bar[XB_XSUB(b.x)], 1u);
;         const unsigned gen = old / nloc;
;         if (old + 1u == (gen + 1u) * nloc) {
;             __builtin_amdgcn_fence(__ATOMIC_RELEASE, "agent");
;             asm volatile("s_waitcnt vmcnt(0)" ::: "memory");
;             const unsigned og = xb_add(&bar[XB_TOP], 1u);
;             const unsigned tg = og / nx;
;             if (og + 1u == (tg + 1u) * nx) xb_add(&bar[XB_TOPGEN], 1u);
;             else XB_SPIN(xb_ld(&bar[XB_TOPGEN]) == tg, bar);
;             __builtin_amdgcn_fence(__ATOMIC_ACQUIRE, "agent");
;             xb_add(&bar[XB_XGEN(b.x)], 1u);
;             asm volatile("s_waitcnt vmcnt(0)" ::: "memory");
;         } else {
;             XB_SPIN(xb_ld(&bar[XB_XGEN(b.x)]) == gen, bar);
.LBB0_295:
	s_or_b64 exec, exec, s[4:5]
	v_cvt_f32_u32_e32 v4, v2
	s_waitcnt vmcnt(0)
	v_readfirstlane_b32 s4, v3
	v_sub_u32_e32 v3, 0, v2
	v_rcp_iflag_f32_e32 v4, v4
	v_add_u32_e32 v5, s4, v1
	v_mul_f32_e32 v4, 0x4f7ffffe, v4
	v_cvt_u32_f32_e32 v4, v4
	v_mul_lo_u32 v1, v3, v4
	v_mul_hi_u32 v1, v4, v1
	v_add_u32_e32 v1, v4, v1
	v_mul_hi_u32 v1, v5, v1
	v_mul_lo_u32 v3, v1, v2
	v_sub_u32_e32 v3, v5, v3
	v_add_u32_e32 v4, 1, v1
	v_cmp_ge_u32_e32 vcc, v3, v2
	s_nop 1
	v_cndmask_b32_e32 v1, v1, v4, vcc
	v_sub_u32_e32 v4, v3, v2
	v_cndmask_b32_e32 v3, v3, v4, vcc
	v_add_u32_e32 v4, 1, v1
	v_cmp_ge_u32_e32 vcc, v3, v2
	v_add_u32_e32 v3, 1, v5
	s_nop 0
	v_cndmask_b32_e32 v1, v1, v4, vcc
	v_mul_lo_u32 v4, v2, v1
	v_add_u32_e32 v2, v4, v2
	v_cmp_ne_u32_e32 vcc, v3, v2
	s_and_saveexec_b64 s[4:5], vcc
	s_xor_b64 s[4:5], exec, s[4:5]
	s_cbranch_execz .LBB0_309
	v_readlane_b32 s10, v254, 55
	v_readlane_b32 s11, v254, 56
	s_waitcnt lgkmcnt(0)
	s_nop 3
	global_load_dword v0, v96, s[10:11] sc1
	s_waitcnt vmcnt(0)
	v_cmp_eq_u32_e32 vcc, v0, v1
	s_and_saveexec_b64 s[14:15], vcc
	s_cbranch_execz .LBB0_308
	s_mov_b32 s9, 1
	s_mov_b64 s[40:41], 0
	s_branch .LBB0_299

; __device__ __forceinline__ unsigned xb_ld(unsigned* p)              { return __hip_atomic_load(p, __ATOMIC_RELAXED, __HIP_MEMORY_SCOPE_AGENT); }
; #define XB_SPIN(cond, bar) do { unsigned _sp = 0; while (cond) { __builtin_amdgcn_s_sleep(1); \
;     if ((++_sp & 255u) == 0u) { if (xb_ld(&(bar)[XB_TMO])) break; if (_sp > XB_SPIN_CAP) { atomicAdd(&(bar)[XB_TMO], 1u); break; } } } } while (0)
; __device__ __forceinline__ void xcd_barrier(const XcdBarrier& b) {
;     ...
;             XB_SPIN(xb_ld(&bar[XB_XGEN(b.x)]) == gen, bar);
.LBB0_301:
	v_readlane_b32 s10, v254, 55
	v_readlane_b32 s11, v254, 56
	s_add_i32 s9, s9, 1
	s_mov_b64 s[48:49], -1
	s_nop 2
	global_load_dword v0, v96, s[10:11] sc1
	s_waitcnt vmcnt(0)
	v_cmp_ne_u32_e32 vcc, v0, v1
	s_orn2_b64 s[46:47], vcc, exec
	s_branch .LBB0_298

; __device__ __forceinline__ unsigned xb_add(unsigned* p, unsigned v) { return __hip_atomic_fetch_add(p, v, __ATOMIC_RELAXED, __HIP_MEMORY_SCOPE_AGENT); }
; __device__ __forceinline__ void xcd_barrier(const XcdBarrier& b) {
;     ...
;             __builtin_amdgcn_fence(__ATOMIC_ACQUIRE, "agent");
;             xb_add(&bar[XB_XGEN(b.x)], 1u);
;             asm volatile("s_waitcnt vmcnt(0)" ::: "memory");
.LBB0_326:
	s_or_b64 exec, exec, s[4:5]
	s_mov_b64 s[4:5], exec
	v_mbcnt_lo_u32_b32 v0, s4, 0
	v_mbcnt_hi_u32_b32 v0, s5, v0
	v_cmp_eq_u32_e32 vcc, 0, v0
	s_waitcnt vmcnt(0)
	buffer_inv sc1
	s_and_saveexec_b64 s[14:15], vcc
	s_cbranch_execz .LBB0_328
	s_bcnt1_i32_b64 s4, s[4:5]
	v_mov_b32_e32 v0, s4
	v_readlane_b32 s4, v254, 51
	v_readlane_b32 s5, v254, 52
	s_nop 4
	s_nop 0

; __device__ __forceinline__ unsigned xb_ld(unsigned* p)              { return __hip_atomic_load(p, __ATOMIC_RELAXED, __HIP_MEMORY_SCOPE_AGENT); }
; __device__ __forceinline__ unsigned xb_add(unsigned* p, unsigned v) { return __hip_atomic_fetch_add(p, v, __ATOMIC_RELAXED, __HIP_MEMORY_SCOPE_AGENT); }
; #define XB_SPIN(cond, bar) do { unsigned _sp = 0; while (cond) { __builtin_amdgcn_s_sleep(1); \
;     if ((++_sp & 255u) == 0u) { if (xb_ld(&(bar)[XB_TMO])) break; if (_sp > XB_SPIN_CAP) { atomicAdd(&(bar)[XB_TMO], 1u); break; } } } } while (0)
; __device__ __forceinline__ void xcd_barrier(const XcdBarrier& b) {
;     ...
;         const unsigned old = xb_add(&bar[XB_XSUB(b.x)], 1u);
;         const unsigned gen = old / nloc;
;         if (old + 1u == (gen + 1u) * nloc) {
;             __builtin_amdgcn_fence(__ATOMIC_RELEASE, "agent");
;             asm volatile("s_waitcnt vmcnt(0)" ::: "memory");
;             const unsigned og = xb_add(&bar[XB_TOP], 1u);
;             const unsigned tg = og / nx;
;             if (og + 1u == (tg + 1u) * nx) xb_add(&bar[XB_TOPGEN], 1u);
;             else XB_SPIN(xb_ld(&bar[XB_TOPGEN]) == tg, bar);
;             __builtin_amdgcn_fence(__ATOMIC_ACQUIRE, "agent");
;             xb_add(&bar[XB_XGEN(b.x)], 1u);
;             asm volatile("s_waitcnt vmcnt(0)" ::: "memory");
;         } else {
;             XB_SPIN(xb_ld(&bar[XB_XGEN(b.x)]) == gen, bar);
.LBB0_389:
	s_or_b64 exec, exec, s[4:5]
	v_cvt_f32_u32_e32 v4, v2
	s_waitcnt vmcnt(0)
	v_readfirstlane_b32 s4, v3
	v_sub_u32_e32 v3, 0, v2
	v_rcp_iflag_f32_e32 v4, v4
	v_add_u32_e32 v5, s4, v1
	v_mul_f32_e32 v4, 0x4f7ffffe, v4
	v_cvt_u32_f32_e32 v4, v4
	v_mul_lo_u32 v1, v3, v4
	v_mul_hi_u32 v1, v4, v1
	v_add_u32_e32 v1, v4, v1
	v_mul_hi_u32 v1, v5, v1
	v_mul_lo_u32 v3, v1, v2
	v_sub_u32_e32 v3, v5, v3
	v_add_u32_e32 v4, 1, v1
	v_cmp_ge_u32_e32 vcc, v3, v2
	s_nop 1
	v_cndmask_b32_e32 v1, v1, v4, vcc
	v_sub_u32_e32 v4, v3, v2
	v_cndmask_b32_e32 v3, v3, v4, vcc
	v_add_u32_e32 v4, 1, v1
	v_cmp_ge_u32_e32 vcc, v3, v2
	v_add_u32_e32 v3, 1, v5
	s_nop 0
	v_cndmask_b32_e32 v1, v1, v4, vcc
	v_mul_lo_u32 v4, v2, v1
	v_add_u32_e32 v2, v4, v2
	v_cmp_ne_u32_e32 vcc, v3, v2
	s_and_saveexec_b64 s[4:5], vcc
	s_xor_b64 s[4:5], exec, s[4:5]
	s_cbranch_execz .LBB0_403
	v_readlane_b32 s8, v254, 55
	v_readlane_b32 s9, v254, 56
	s_waitcnt lgkmcnt(0)
	s_nop 3
	global_load_dword v0, v96, s[8:9] sc1
	s_waitcnt vmcnt(0)
	v_cmp_eq_u32_e32 vcc, v0, v1
	s_and_saveexec_b64 s[14:15], vcc
	s_cbranch_execz .LBB0_402
	s_mov_b32 s8, 1
	s_mov_b64 s[42:43], 0
	s_branch .LBB0_393

; __device__ __forceinline__ unsigned xb_ld(unsigned* p)              { return __hip_atomic_load(p, __ATOMIC_RELAXED, __HIP_MEMORY_SCOPE_AGENT); }
; #define XB_SPIN(cond, bar) do { unsigned _sp = 0; while (cond) { __builtin_amdgcn_s_sleep(1); \
;     if ((++_sp & 255u) == 0u) { if (xb_ld(&(bar)[XB_TMO])) break; if (_sp > XB_SPIN_CAP) { atomicAdd(&(bar)[XB_TMO], 1u); break; } } } } while (0)
; __device__ __forceinline__ void xcd_barrier(const XcdBarrier& b) {
;     ...
;             XB_SPIN(xb_ld(&bar[XB_XGEN(b.x)]) == gen, bar);
.LBB0_395:
	v_readlane_b32 s10, v254, 55
	v_readlane_b32 s11, v254, 56
	s_add_i32 s8, s8, 1
	s_mov_b64 s[48:49], -1
	s_nop 2
	global_load_dword v0, v96, s[10:11] sc1
	s_waitcnt vmcnt(0)
	v_cmp_ne_u32_e32 vcc, v0, v1
	s_orn2_b64 s[46:47], vcc, exec
	s_branch .LBB0_392

; __device__ __forceinline__ unsigned xb_ld(unsigned* p)              { return __hip_atomic_load(p, __ATOMIC_RELAXED, __HIP_MEMORY_SCOPE_AGENT); }
; #define XB_SPIN(cond, bar) do { unsigned _sp = 0; while (cond) { __builtin_amdgcn_s_sleep(1); \
;     if ((++_sp & 255u) == 0u) { if (xb_ld(&(bar)[XB_TMO])) break; if (_sp > XB_SPIN_CAP) { atomicAdd(&(bar)[XB_TMO], 1u); break; } } } } while (0)
; __device__ __forceinline__ void xcd_barrier(const XcdBarrier& b) {
;     ...
;             XB_SPIN(xb_ld(&bar[XB_XGEN(b.x)]) == gen, bar);
.LBB0_477:
	v_readlane_b32 s10, v254, 55
	v_readlane_b32 s11, v254, 56
	s_add_i32 s9, s9, 1
	s_mov_b64 s[46:47], -1
	s_nop 2
	global_load_dword v0, v96, s[10:11] sc1
	s_waitcnt vmcnt(0)
	v_cmp_ne_u32_e32 vcc, v0, v1
	s_orn2_b64 s[44:45], vcc, exec
	s_branch .LBB0_474

; __device__ __forceinline__ unsigned xb_ld(unsigned* p)              { return __hip_atomic_load(p, __ATOMIC_RELAXED, __HIP_MEMORY_SCOPE_AGENT); }
; __device__ __forceinline__ unsigned xb_add(unsigned* p, unsigned v) { return __hip_atomic_fetch_add(p, v, __ATOMIC_RELAXED, __HIP_MEMORY_SCOPE_AGENT); }
; #define XB_SPIN(cond, bar) do { unsigned _sp = 0; while (cond) { __builtin_amdgcn_s_sleep(1); \
;     if ((++_sp & 255u) == 0u) { if (xb_ld(&(bar)[XB_TMO])) break; if (_sp > XB_SPIN_CAP) { atomicAdd(&(bar)[XB_TMO], 1u); break; } } } } while (0)
; __device__ __forceinline__ void xcd_barrier(const XcdBarrier& b) {
;     ...
;         const unsigned old = xb_add(&bar[XB_XSUB(b.x)], 1u);
;         const unsigned gen = old / nloc;
;         if (old + 1u == (gen + 1u) * nloc) {
;             __builtin_amdgcn_fence(__ATOMIC_RELEASE, "agent");
;             asm volatile("s_waitcnt vmcnt(0)" ::: "memory");
;             const unsigned og = xb_add(&bar[XB_TOP], 1u);
;             const unsigned tg = og / nx;
;             if (og + 1u == (tg + 1u) * nx) xb_add(&bar[XB_TOPGEN], 1u);
;             else XB_SPIN(xb_ld(&bar[XB_TOPGEN]) == tg, bar);
;             __builtin_amdgcn_fence(__ATOMIC_ACQUIRE, "agent");
;             xb_add(&bar[XB_XGEN(b.x)], 1u);
;             asm volatile("s_waitcnt vmcnt(0)" ::: "memory");
;         } else {
;             XB_SPIN(xb_ld(&bar[XB_XGEN(b.x)]) == gen, bar);
.LBB0_822:
	s_or_b64 exec, exec, s[4:5]
	v_cvt_f32_u32_e32 v4, v2
	s_waitcnt vmcnt(0)
	v_readfirstlane_b32 s4, v3
	v_sub_u32_e32 v3, 0, v2
	v_rcp_iflag_f32_e32 v4, v4
	v_add_u32_e32 v5, s4, v1
	v_mul_f32_e32 v4, 0x4f7ffffe, v4
	v_cvt_u32_f32_e32 v4, v4
	v_mul_lo_u32 v1, v3, v4
	v_mul_hi_u32 v1, v4, v1
	v_add_u32_e32 v1, v4, v1
	v_mul_hi_u32 v1, v5, v1
	v_mul_lo_u32 v3, v1, v2
	v_sub_u32_e32 v3, v5, v3
	v_add_u32_e32 v4, 1, v1
	v_cmp_ge_u32_e32 vcc, v3, v2
	s_nop 1
	v_cndmask_b32_e32 v1, v1, v4, vcc
	v_sub_u32_e32 v4, v3, v2
	v_cndmask_b32_e32 v3, v3, v4, vcc
	v_add_u32_e32 v4, 1, v1
	v_cmp_ge_u32_e32 vcc, v3, v2
	v_add_u32_e32 v3, 1, v5
	s_nop 0
	v_cndmask_b32_e32 v1, v1, v4, vcc
	v_mul_lo_u32 v4, v2, v1
	v_add_u32_e32 v2, v4, v2
	v_cmp_ne_u32_e32 vcc, v3, v2
	s_and_saveexec_b64 s[4:5], vcc
	s_xor_b64 s[4:5], exec, s[4:5]
	s_cbranch_execz .LBB0_836
	v_readlane_b32 s6, v254, 55
	v_readlane_b32 s7, v254, 56
	s_waitcnt lgkmcnt(0)
	s_nop 3
	global_load_dword v0, v96, s[6:7] sc1
	s_waitcnt vmcnt(0)
	v_cmp_eq_u32_e32 vcc, v0, v1
	s_and_saveexec_b64 s[14:15], vcc
	s_cbranch_execz .LBB0_835
	s_mov_b32 s6, 1
	s_mov_b64 s[40:41], 0
	s_branch .LBB0_826

; __device__ __forceinline__ unsigned xb_ld(unsigned* p)              { return __hip_atomic_load(p, __ATOMIC_RELAXED, __HIP_MEMORY_SCOPE_AGENT); }
; #define XB_SPIN(cond, bar) do { unsigned _sp = 0; while (cond) { __builtin_amdgcn_s_sleep(1); \
;     if ((++_sp & 255u) == 0u) { if (xb_ld(&(bar)[XB_TMO])) break; if (_sp > XB_SPIN_CAP) { atomicAdd(&(bar)[XB_TMO], 1u); break; } } } } while (0)
; __device__ __forceinline__ void xcd_barrier(const XcdBarrier& b) {
;     ...
;             XB_SPIN(xb_ld(&bar[XB_XGEN(b.x)]) == gen, bar);
.LBB0_828:
	v_readlane_b32 s8, v254, 55
	v_readlane_b32 s9, v254, 56
	s_add_i32 s6, s6, 1
	s_mov_b64 s[46:47], -1
	s_nop 2
	global_load_dword v0, v96, s[8:9] sc1
	s_waitcnt vmcnt(0)
	v_cmp_ne_u32_e32 vcc, v0, v1
	s_orn2_b64 s[44:45], vcc, exec
	s_branch .LBB0_825

; __device__ __forceinline__ unsigned xb_ld(unsigned* p)              { return __hip_atomic_load(p, __ATOMIC_RELAXED, __HIP_MEMORY_SCOPE_AGENT); }
; __device__ __forceinline__ unsigned xb_add(unsigned* p, unsigned v) { return __hip_atomic_fetch_add(p, v, __ATOMIC_RELAXED, __HIP_MEMORY_SCOPE_AGENT); }
; #define XB_SPIN(cond, bar) do { unsigned _sp = 0; while (cond) { __builtin_amdgcn_s_sleep(1); \
;     if ((++_sp & 255u) == 0u) { if (xb_ld(&(bar)[XB_TMO])) break; if (_sp > XB_SPIN_CAP) { atomicAdd(&(bar)[XB_TMO], 1u); break; } } } } while (0)
; __device__ __forceinline__ void xcd_barrier(const XcdBarrier& b) {
;     ...
;         const unsigned old = xb_add(&bar[XB_XSUB(b.x)], 1u);
;         const unsigned gen = old / nloc;
;         if (old + 1u == (gen + 1u) * nloc) {
;             __builtin_amdgcn_fence(__ATOMIC_RELEASE, "agent");
;             asm volatile("s_waitcnt vmcnt(0)" ::: "memory");
;             const unsigned og = xb_add(&bar[XB_TOP], 1u);
;             const unsigned tg = og / nx;
;             if (og + 1u == (tg + 1u) * nx) xb_add(&bar[XB_TOPGEN], 1u);
;             else XB_SPIN(xb_ld(&bar[XB_TOPGEN]) == tg, bar);
;             __builtin_amdgcn_fence(__ATOMIC_ACQUIRE, "agent");
;             xb_add(&bar[XB_XGEN(b.x)], 1u);
;             asm volatile("s_waitcnt vmcnt(0)" ::: "memory");
;         } else {
;             XB_SPIN(xb_ld(&bar[XB_XGEN(b.x)]) == gen, bar);
.LBB0_934:
	s_or_b64 exec, exec, s[4:5]
	v_cvt_f32_u32_e32 v4, v2
	s_waitcnt vmcnt(0)
	v_readfirstlane_b32 s4, v3
	v_sub_u32_e32 v3, 0, v2
	v_rcp_iflag_f32_e32 v4, v4
	v_add_u32_e32 v5, s4, v1
	v_mul_f32_e32 v4, 0x4f7ffffe, v4
	v_cvt_u32_f32_e32 v4, v4
	v_mul_lo_u32 v1, v3, v4
	v_mul_hi_u32 v1, v4, v1
	v_add_u32_e32 v1, v4, v1
	v_mul_hi_u32 v1, v5, v1
	v_mul_lo_u32 v3, v1, v2
	v_sub_u32_e32 v3, v5, v3
	v_add_u32_e32 v4, 1, v1
	v_cmp_ge_u32_e32 vcc, v3, v2
	s_nop 1
	v_cndmask_b32_e32 v1, v1, v4, vcc
	v_sub_u32_e32 v4, v3, v2
	v_cndmask_b32_e32 v3, v3, v4, vcc
	v_add_u32_e32 v4, 1, v1
	v_cmp_ge_u32_e32 vcc, v3, v2
	v_add_u32_e32 v3, 1, v5
	s_nop 0
	v_cndmask_b32_e32 v1, v1, v4, vcc
	v_mul_lo_u32 v4, v2, v1
	v_add_u32_e32 v2, v4, v2
	v_cmp_ne_u32_e32 vcc, v3, v2
	s_and_saveexec_b64 s[4:5], vcc
	s_xor_b64 s[4:5], exec, s[4:5]
	s_cbranch_execz .LBB0_948
	v_readlane_b32 s8, v254, 55
	v_readlane_b32 s9, v254, 56
	s_waitcnt lgkmcnt(0)
	s_nop 3
	global_load_dword v0, v96, s[8:9] sc1
	s_waitcnt vmcnt(0)
	v_cmp_eq_u32_e32 vcc, v0, v1
	s_and_saveexec_b64 s[14:15], vcc
	s_cbranch_execz .LBB0_947
	s_mov_b32 s7, 1
	s_mov_b64 s[40:41], 0
	s_branch .LBB0_938

; __device__ __forceinline__ unsigned xb_ld(unsigned* p)              { return __hip_atomic_load(p, __ATOMIC_RELAXED, __HIP_MEMORY_SCOPE_AGENT); }
; #define XB_SPIN(cond, bar) do { unsigned _sp = 0; while (cond) { __builtin_amdgcn_s_sleep(1); \
;     if ((++_sp & 255u) == 0u) { if (xb_ld(&(bar)[XB_TMO])) break; if (_sp > XB_SPIN_CAP) { atomicAdd(&(bar)[XB_TMO], 1u); break; } } } } while (0)
; __device__ __forceinline__ void xcd_barrier(const XcdBarrier& b) {
;     ...
;             XB_SPIN(xb_ld(&bar[XB_XGEN(b.x)]) == gen, bar);
.LBB0_940:
	v_readlane_b32 s8, v254, 55
	v_readlane_b32 s9, v254, 56
	s_add_i32 s7, s7, 1
	s_mov_b64 s[46:47], -1
	s_nop 2
	global_load_dword v0, v96, s[8:9] sc1
	s_waitcnt vmcnt(0)
	v_cmp_ne_u32_e32 vcc, v0, v1
	s_orn2_b64 s[44:45], vcc, exec
	s_branch .LBB0_937

; __device__ __forceinline__ unsigned xb_ld(unsigned* p)              { return __hip_atomic_load(p, __ATOMIC_RELAXED, __HIP_MEMORY_SCOPE_AGENT); }
; __device__ __forceinline__ unsigned xb_add(unsigned* p, unsigned v) { return __hip_atomic_fetch_add(p, v, __ATOMIC_RELAXED, __HIP_MEMORY_SCOPE_AGENT); }
; #define XB_SPIN(cond, bar) do { unsigned _sp = 0; while (cond) { __builtin_amdgcn_s_sleep(1); \
;     if ((++_sp & 255u) == 0u) { if (xb_ld(&(bar)[XB_TMO])) break; if (_sp > XB_SPIN_CAP) { atomicAdd(&(bar)[XB_TMO], 1u); break; } } } } while (0)
; __device__ __forceinline__ void xcd_barrier(const XcdBarrier& b) {
;     ...
;         const unsigned old = xb_add(&bar[XB_XSUB(b.x)], 1u);
;         const unsigned gen = old / nloc;
;         if (old + 1u == (gen + 1u) * nloc) {
;             __builtin_amdgcn_fence(__ATOMIC_RELEASE, "agent");
;             asm volatile("s_waitcnt vmcnt(0)" ::: "memory");
;             const unsigned og = xb_add(&bar[XB_TOP], 1u);
;             const unsigned tg = og / nx;
;             if (og + 1u == (tg + 1u) * nx) xb_add(&bar[XB_TOPGEN], 1u);
;             else XB_SPIN(xb_ld(&bar[XB_TOPGEN]) == tg, bar);
;             __builtin_amdgcn_fence(__ATOMIC_ACQUIRE, "agent");
;             xb_add(&bar[XB_XGEN(b.x)], 1u);
;             asm volatile("s_waitcnt vmcnt(0)" ::: "memory");
;         } else {
;             XB_SPIN(xb_ld(&bar[XB_XGEN(b.x)]) == gen, bar);
.LBB0_1255:
	s_or_b64 exec, exec, s[2:3]
	v_cvt_f32_u32_e32 v4, v2
	s_waitcnt vmcnt(0)
	v_readfirstlane_b32 s2, v3
	v_sub_u32_e32 v3, 0, v2
	v_rcp_iflag_f32_e32 v4, v4
	v_add_u32_e32 v5, s2, v1
	v_mul_f32_e32 v4, 0x4f7ffffe, v4
	v_cvt_u32_f32_e32 v4, v4
	v_mul_lo_u32 v1, v3, v4
	v_mul_hi_u32 v1, v4, v1
	v_add_u32_e32 v1, v4, v1
	v_mul_hi_u32 v1, v5, v1
	v_mul_lo_u32 v3, v1, v2
	v_sub_u32_e32 v3, v5, v3
	v_add_u32_e32 v4, 1, v1
	v_cmp_ge_u32_e32 vcc, v3, v2
	s_nop 1
	v_cndmask_b32_e32 v1, v1, v4, vcc
	v_sub_u32_e32 v4, v3, v2
	v_cndmask_b32_e32 v3, v3, v4, vcc
	v_add_u32_e32 v4, 1, v1
	v_cmp_ge_u32_e32 vcc, v3, v2
	v_add_u32_e32 v3, 1, v5
	s_nop 0
	v_cndmask_b32_e32 v1, v1, v4, vcc
	v_mul_lo_u32 v4, v2, v1
	v_add_u32_e32 v2, v4, v2
	v_cmp_ne_u32_e32 vcc, v3, v2
	s_and_saveexec_b64 s[2:3], vcc
	s_xor_b64 s[2:3], exec, s[2:3]
	s_cbranch_execz .LBB0_1269
	v_readlane_b32 s4, v254, 55
	s_waitcnt lgkmcnt(0)
	v_mov_b32_e32 v0, 0
	v_readlane_b32 s5, v254, 56
	s_nop 4
	global_load_dword v2, v0, s[4:5] sc1
	s_waitcnt vmcnt(0)
	v_cmp_eq_u32_e32 vcc, v2, v1
	s_and_saveexec_b64 s[4:5], vcc
	s_cbranch_execz .LBB0_1268
	s_mov_b32 s16, 1
	s_mov_b64 s[6:7], 0
	s_branch .LBB0_1259

; __device__ __forceinline__ unsigned xb_ld(unsigned* p)              { return __hip_atomic_load(p, __ATOMIC_RELAXED, __HIP_MEMORY_SCOPE_AGENT); }
; #define XB_SPIN(cond, bar) do { unsigned _sp = 0; while (cond) { __builtin_amdgcn_s_sleep(1); \
;     if ((++_sp & 255u) == 0u) { if (xb_ld(&(bar)[XB_TMO])) break; if (_sp > XB_SPIN_CAP) { atomicAdd(&(bar)[XB_TMO], 1u); break; } } } } while (0)
; __device__ __forceinline__ void xcd_barrier(const XcdBarrier& b) {
;     ...
;             XB_SPIN(xb_ld(&bar[XB_XGEN(b.x)]) == gen, bar);
.LBB0_1261:
	v_readlane_b32 s10, v254, 55
	v_readlane_b32 s11, v254, 56
	s_add_i32 s16, s16, 1
	s_mov_b64 s[12:13], -1
	s_nop 2
	global_load_dword v2, v0, s[10:11] sc1
	s_waitcnt vmcnt(0)
	v_cmp_ne_u32_e32 vcc, v2, v1
	s_orn2_b64 s[10:11], vcc, exec
	s_branch .LBB0_1258

; __device__ __forceinline__ unsigned xb_add(unsigned* p, unsigned v) { return __hip_atomic_fetch_add(p, v, __ATOMIC_RELAXED, __HIP_MEMORY_SCOPE_AGENT); }
; __device__ __forceinline__ void xcd_barrier(const XcdBarrier& b) {
;     ...
;             __builtin_amdgcn_fence(__ATOMIC_ACQUIRE, "agent");
;             xb_add(&bar[XB_XGEN(b.x)], 1u);
;             asm volatile("s_waitcnt vmcnt(0)" ::: "memory");
.LBB0_1286:
	s_or_b64 exec, exec, s[2:3]
	s_mov_b64 s[2:3], exec
	v_mbcnt_lo_u32_b32 v0, s2, 0
	v_mbcnt_hi_u32_b32 v0, s3, v0
	v_cmp_eq_u32_e32 vcc, 0, v0
	s_waitcnt vmcnt(0)
	buffer_inv sc1
	s_and_saveexec_b64 s[4:5], vcc
	s_cbranch_execz .LBB0_1288
	s_bcnt1_i32_b64 s2, s[2:3]
	v_mov_b32_e32 v1, s2
	v_readlane_b32 s2, v254, 51
	v_mov_b32_e32 v0, 0
	v_readlane_b32 s3, v254, 52
	s_nop 4
	s_nop 0
